# grid barrier: non-leader L1 invalidate issued while polling instead of after release
# speedup vs baseline: 1.0760x; 1.0049x over previous
.LBB0_1206:
	v_readlane_b32 s2, v254, 3
	v_readlane_b32 s3, v254, 4
	v_cvt_f32_u32_e32 v1, v2
	v_sub_u32_e32 v4, 0, v2
	v_rcp_iflag_f32_e32 v1, v1
	s_nop 1
	global_atomic_add v3, v33, v179, s[2:3] sc0
	v_mul_f32_e32 v1, 0x4f7ffffe, v1
	v_cvt_u32_f32_e32 v1, v1
	v_mul_lo_u32 v4, v4, v1
	v_mul_hi_u32 v4, v1, v4
	v_add_u32_e32 v1, v1, v4
	s_waitcnt vmcnt(0)
	v_mul_hi_u32 v1, v3, v1
	v_mul_lo_u32 v4, v1, v2
	v_sub_u32_e32 v4, v3, v4
	v_add_u32_e32 v5, 1, v1
	v_cmp_ge_u32_e32 vcc, v4, v2
	v_add_u32_e32 v3, 1, v3
	s_nop 0
	v_cndmask_b32_e32 v1, v1, v5, vcc
	v_sub_u32_e32 v5, v4, v2
	v_cndmask_b32_e32 v4, v4, v5, vcc
	v_add_u32_e32 v5, 1, v1
	v_cmp_ge_u32_e32 vcc, v4, v2
	s_nop 1
	v_cndmask_b32_e32 v1, v1, v5, vcc
	v_mul_lo_u32 v4, v2, v1
	v_add_u32_e32 v2, v4, v2
	v_cmp_ne_u32_e32 vcc, v3, v2
	s_and_saveexec_b64 s[2:3], vcc
	s_xor_b64 s[26:27], exec, s[2:3]
	s_cbranch_execz .LBB0_1220
	v_readlane_b32 s2, v254, 5
	v_readlane_b32 s3, v254, 6
	s_waitcnt lgkmcnt(0)
	s_nop 3
	buffer_inv sc1
	global_load_dword v0, v33, s[2:3] sc1
	s_waitcnt vmcnt(0)
	v_cmp_eq_u32_e32 vcc, v0, v1
	s_and_saveexec_b64 s[34:35], vcc
	s_cbranch_execz .LBB0_1219
	s_mov_b32 s0, 1
	s_mov_b64 s[38:39], 0
	s_branch .LBB0_1210

.LBB0_1219:
	s_or_b64 exec, exec, s[34:35]
	s_waitcnt vmcnt(0)
.LBB0_1220:
	s_andn2_saveexec_b64 s[2:3], s[26:27]
	s_cbranch_execnz .LBB0_1221
	s_getpc_b64 s[98:99]
